# attention MODE0 steady loop: first two QK mfma of each step issued before the preceding step barrier (register-only operands), C-init mfma one gap earlier
# speedup vs baseline: 1.0060x; 1.0060x over previous
.LBB0_796:
	v_lshlrev_b32_e32 v53, 1, v52
	v_lshlrev_b32_e32 v52, 4, v52
	v_and_b32_e32 v214, 32, v53
	v_and_b32_e32 v52, 0xc0, v52
	v_lshl_or_b32 v213, v209, 8, v52
	v_add_u32_e32 v52, 0, v214
	v_add3_u32 v219, v52, v211, v213
	v_max3_f32 v52, v36, v37, v20
	v_max3_f32 v53, v38, v39, v21
	s_and_b32 s0, s22, 0x3fffffc0
	v_max3_f32 v52, v52, v22, v23
	v_max3_f32 v53, v53, v42, v43
	s_lshl_b32 s0, s0, 2
	v_max3_f32 v52, v52, v40, v41
	v_max3_f32 v53, v53, v26, v27
	s_add_i32 s1, s64, 0x100
	v_max3_f32 v52, v52, v24, v25
	v_max3_f32 v53, v53, v46, v47
	s_add_i32 s53, s0, 0
	v_max3_f32 v52, v52, v44, v45
	v_max3_f32 v53, v53, v30, v31
	s_lshr_b32 s48, s1, 6
	v_max3_f32 v52, v52, v28, v29
	v_max3_f32 v53, v53, v50, v51
	s_mov_b64 s[22:23], 0x60000
	v_max3_f32 v52, v52, v48, v49
	v_max3_f32 v53, v53, v34, v35
	s_cmp_lg_u32 0, -1
	v_max3_f32 v52, v52, v32, v33
	s_mov_b64 s[10:11], 0x20000
	v_max_f32_e32 v52, v52, v53
	v_lshl_add_u64 v[190:191], v[84:85], 0, s[10:11]
	v_mov_b32_e32 v53, v52
	s_nop 1
	v_permlane32_swap_b32_e32 v52, v53
	v_max_f32_e32 v52, v52, v53
	s_mov_b32 s0, 1
	v_max_f32_e32 v52, v52, v228
	s_mov_b32 s24, 0
	v_add_f32_e32 v217, v3, v52
	v_sub_f32_e32 v53, v36, v52
	v_sub_f32_e32 v54, v37, v52
	v_sub_f32_e32 v55, v38, v52
	v_sub_f32_e32 v56, v39, v52
	v_sub_f32_e32 v57, v40, v52
	s_nop 0
	v_xor_b32_e32 v36, 0x80000000, v217
	v_sub_f32_e32 v58, v41, v52
	v_sub_f32_e32 v59, v42, v52
	v_sub_f32_e32 v60, v43, v52
	v_sub_f32_e32 v61, v44, v52
	v_sub_f32_e32 v62, v45, v52
	v_sub_f32_e32 v63, v46, v52
	v_sub_f32_e32 v64, v47, v52
	v_sub_f32_e32 v65, v48, v52
	v_sub_f32_e32 v66, v49, v52
	v_sub_f32_e32 v67, v50, v52
	v_sub_f32_e32 v83, v51, v52
	v_mov_b32_e32 v37, v36
	v_mov_b32_e32 v38, v36
	v_mov_b32_e32 v39, v36
	v_mov_b32_e32 v40, v36
	v_mov_b32_e32 v41, v36
	v_mov_b32_e32 v42, v36
	v_mov_b32_e32 v43, v36
	v_mov_b32_e32 v44, v36
	v_mov_b32_e32 v45, v36
	v_mov_b32_e32 v46, v36
	v_mov_b32_e32 v47, v36
	v_mov_b32_e32 v48, v36
	v_mov_b32_e32 v49, v36
	v_mov_b32_e32 v50, v36
	v_mov_b32_e32 v51, v36
	v_sub_f32_e32 v20, v20, v52
	v_sub_f32_e32 v21, v21, v52
	s_waitcnt vmcnt(0) lgkmcnt(0)
	s_barrier
	v_sub_f32_e32 v22, v22, v52
	v_sub_f32_e32 v23, v23, v52
	v_sub_f32_e32 v24, v24, v52
	v_sub_f32_e32 v25, v25, v52
	v_sub_f32_e32 v26, v26, v52
	v_sub_f32_e32 v27, v27, v52
	v_sub_f32_e32 v28, v28, v52
	v_sub_f32_e32 v29, v29, v52
	v_sub_f32_e32 v30, v30, v52
	v_sub_f32_e32 v31, v31, v52
	v_sub_f32_e32 v32, v32, v52
	v_sub_f32_e32 v33, v33, v52
	v_sub_f32_e32 v34, v34, v52
	v_sub_f32_e32 v35, v35, v52
	v_exp_f32_e32 v68, v53
	v_exp_f32_e32 v52, v20
	v_exp_f32_e32 v53, v21
	v_lshl_add_u64 v[20:21], v[188:189], 0, s[22:23]
	s_mov_b32 m0, s46
	s_nop 0
	global_load_lds_dwordx4 v[20:21], off
	s_cselect_b32 s1, 0, 0
	s_add_i32 s1, s1, s45
	s_add_i32 s1, s1, 0x8000
	s_mov_b32 m0, s1
	s_nop 0
	global_load_lds_dwordx4 v[190:191], off
	ds_read_b128 v[180:183], v218 offset:8192
	ds_read_b128 v[176:179], v218 offset:8704
	ds_read_b128 v[172:175], v218 offset:10240
	ds_read_b128 v[168:171], v218 offset:10752
	ds_read_b128 v[164:167], v218 offset:12288
	ds_read_b128 v[160:163], v218 offset:12800
	ds_read_b128 v[156:159], v218 offset:14336
	ds_read_b128 v[152:155], v218 offset:14848
	v_exp_f32_e32 v69, v54
	v_exp_f32_e32 v70, v55
	v_exp_f32_e32 v71, v56
	v_exp_f32_e32 v72, v57
	v_exp_f32_e32 v73, v58
	v_exp_f32_e32 v74, v59
	v_exp_f32_e32 v75, v60
	v_exp_f32_e32 v76, v61
	v_exp_f32_e32 v77, v62
	v_exp_f32_e32 v78, v63
	v_exp_f32_e32 v79, v64
	v_exp_f32_e32 v80, v65
	v_exp_f32_e32 v81, v66
	v_exp_f32_e32 v82, v67
	v_exp_f32_e32 v83, v83
	v_exp_f32_e32 v54, v22
	v_exp_f32_e32 v55, v23
	v_exp_f32_e32 v56, v24
	v_exp_f32_e32 v57, v25
	v_exp_f32_e32 v58, v26
	v_exp_f32_e32 v59, v27
	v_exp_f32_e32 v60, v28
	v_exp_f32_e32 v61, v29
	v_exp_f32_e32 v62, v30
	v_exp_f32_e32 v63, v31
	v_exp_f32_e32 v64, v32
	v_exp_f32_e32 v65, v33
	v_exp_f32_e32 v66, v34
	v_exp_f32_e32 v67, v35
	s_waitcnt vmcnt(2) lgkmcnt(0)
	s_barrier
	s_andn2_b64 vcc, exec, s[4:5]
	v_cmp_gt_u32_e64 s[4:5], 32, v1
	s_cbranch_vccnz .LBB0_812
	v_lshlrev_b32_e32 v20, 4, v209
	s_mov_b64 s[10:11], 0xa0000
	v_add_u32_e32 v203, s53, v20
	v_mov_b64_e32 v[34:35], v[18:19]
	s_add_i32 s1, s48, -5
	v_lshl_add_u32 v202, v208, 2, s53
	v_lshl_add_u64 v[192:193], v[84:85], 0, s[22:23]
	v_lshl_add_u64 v[194:195], v[188:189], 0, s[10:11]
	s_movk_i32 s24, 0x4000
	s_movk_i32 s25, 0x2000
	s_mov_b32 s10, 0
	v_mov_b32_e32 v220, 0
	v_mov_b64_e32 v[32:33], v[16:17]
	v_mov_b64_e32 v[30:31], v[14:15]
	v_mov_b64_e32 v[28:29], v[12:13]
	v_mov_b64_e32 v[26:27], v[10:11]
	v_mov_b64_e32 v[24:25], v[8:9]
	v_mov_b64_e32 v[22:23], v[6:7]
	v_mov_b64_e32 v[20:21], v[4:5]
	s_mov_b64 s[98:99], exec
	v_and_b32_e32 v224, 0xffff0000, v36
	v_sub_f32_e32 v225, v224, v36
	v_exp_f32_e32 v225, v225
	v_bfe_i32 v196, v132, 0, 1
	v_mov_b32_e32 v250, 0
	v_mov_b32_e32 v251, 0
	v_mov_b32_e32 v252, 0
	v_mov_b32_e32 v253, 0
	v_mov_b32_e32 v247, 0
	v_mov_b32_e32 v248, 0
	v_mov_b32_e32 v249, 0
	v_mov_b32_e32 v222, 0
	v_mov_b32_e32 v223, 0
	s_mov_b32 exec_hi, 0
	v_mov_b32_e32 v250, 0x3f80
	v_mov_b32_e32 v223, 0xf180
	v_lshrrev_b32_e32 v222, 16, v224
	s_mov_b64 exec, s[98:99]
	v_readfirstlane_b32 s98, v192
	v_readfirstlane_b32 s99, v193
	s_sub_u32 s98, s98, 0x1000000
	s_subb_u32 s99, s99, 0
	v_subrev_u32_e32 v199, s98, v192
	v_subrev_u32_e32 v198, s98, v194
	v_add_u32_e32 v203, 0xfffe0000, v199
	v_add_u32_e32 v202, 0xfffe0000, v198
	v_and_b32_e32 v224, v225, v196
	v_mul_f32_e32 v4, v225, v4
	v_mul_f32_e32 v5, v225, v5
	v_mul_f32_e32 v6, v225, v6
	v_mul_f32_e32 v7, v225, v7
	v_mul_f32_e32 v8, v225, v8
	v_mul_f32_e32 v9, v225, v9
	v_mul_f32_e32 v10, v225, v10
	v_mul_f32_e32 v11, v225, v11
	v_mul_f32_e32 v12, v225, v12
	v_mul_f32_e32 v13, v225, v13
	v_mul_f32_e32 v14, v225, v14
	v_mul_f32_e32 v15, v225, v15
	v_mul_f32_e32 v16, v225, v16
	v_mul_f32_e32 v17, v225, v17
	v_mul_f32_e32 v18, v225, v18
	v_mul_f32_e32 v19, v225, v19
	v_mul_f32_e32 v20, v225, v20
	v_mul_f32_e32 v21, v225, v21
	v_mul_f32_e32 v22, v225, v22
	v_mul_f32_e32 v23, v225, v23
	v_mul_f32_e32 v24, v225, v24
	v_mul_f32_e32 v25, v225, v25
	v_mul_f32_e32 v26, v225, v26
	v_mul_f32_e32 v27, v225, v27
	v_mul_f32_e32 v28, v225, v28
	v_mul_f32_e32 v29, v225, v29
	v_mul_f32_e32 v30, v225, v30
	v_mul_f32_e32 v31, v225, v31
	v_mul_f32_e32 v32, v225, v32
	v_mul_f32_e32 v33, v225, v33
	v_mul_f32_e32 v34, v225, v34
	v_mul_f32_e32 v35, v225, v35
	v_mul_f32_e32 v52, v224, v52
	v_mul_f32_e32 v53, v224, v53
	v_mul_f32_e32 v54, v224, v54
	v_mul_f32_e32 v55, v224, v55
	v_mul_f32_e32 v56, v224, v56
	v_mul_f32_e32 v57, v224, v57
	v_mul_f32_e32 v58, v224, v58
	v_mul_f32_e32 v59, v224, v59
	v_mul_f32_e32 v60, v224, v60
	v_mul_f32_e32 v61, v224, v61
	v_mul_f32_e32 v62, v224, v62
	v_mul_f32_e32 v63, v224, v63
	v_mul_f32_e32 v64, v224, v64
	v_mul_f32_e32 v65, v224, v65
	v_mul_f32_e32 v66, v224, v66
	v_mul_f32_e32 v67, v224, v67
	v_mul_f32_e32 v68, v224, v68
	v_mul_f32_e32 v69, v224, v69
	v_mul_f32_e32 v70, v224, v70
	v_mul_f32_e32 v71, v224, v71
	v_mul_f32_e32 v72, v224, v72
	v_mul_f32_e32 v73, v224, v73
	v_mul_f32_e32 v74, v224, v74
	v_mul_f32_e32 v75, v224, v75
	v_mul_f32_e32 v76, v224, v76
	v_mul_f32_e32 v77, v224, v77
	v_mul_f32_e32 v78, v224, v78
	v_mul_f32_e32 v79, v224, v79
	v_mul_f32_e32 v80, v224, v80
	v_mul_f32_e32 v81, v224, v81
	v_mul_f32_e32 v82, v224, v82
	v_mul_f32_e32 v83, v224, v83
	v_mul_f32_e32 v220, v225, v220
	v_bfe_i32 v196, v132, 1, 1
	v_bfi_b32 v246, v196, v222, v223
	s_mov_b32 s101, 2
	s_nop 1
	v_mfma_f32_32x32x16_bf16 v[36:51], v[250:253], v[246:249], 0
	v_mfma_f32_32x32x16_bf16 v[100:115], v[180:183], v[116:119], v[36:51]
	v_mfma_f32_32x32x16_bf16 v[84:99], v[176:179], v[116:119], v[36:51]
	s_branch .LBB0_798
.Lattn0_head:
	s_waitcnt lgkmcnt(0)
	v_mfma_f32_32x32x16_bf16 v[100:115], v[180:183], v[116:119], v[36:51]
	v_mfma_f32_32x32x16_bf16 v[84:99], v[176:179], v[116:119], v[36:51]
	s_waitcnt vmcnt(2) lgkmcnt(0)
	s_barrier
.LBB0_798:
	v_add_u32_e32 v197, s10, v219
	ds_read_b64_tr_b16 v[184:185], v197 offset:24576
	ds_read_b64_tr_b16 v[186:187], v197 offset:25088
	v_add_f32_e32 v205, v68, v69
	v_add_f32_e32 v205, v70, v205
	v_add_f32_e32 v205, v71, v205
	v_cvt_pk_bf16_f32 v148, v68, v69
	v_add_f32_e32 v205, v72, v205
	v_cvt_pk_bf16_f32 v149, v70, v71
	v_add_f32_e32 v205, v73, v205
	ds_read_b64_tr_b16 v[180:181], v197 offset:28672
	ds_read_b64_tr_b16 v[182:183], v197 offset:29184
	v_add_f32_e32 v68, v74, v205
	v_add_f32_e32 v68, v75, v68
	v_add_f32_e32 v68, v76, v68
	v_add_f32_e32 v136, v77, v68
	v_cvt_pk_bf16_f32 v150, v72, v73
	v_cvt_pk_bf16_f32 v151, v74, v75
	ds_read_b64_tr_b16 v[68:69], v197 offset:25600
	ds_read_b64_tr_b16 v[70:71], v197 offset:26112
	v_mfma_f32_32x32x16_bf16 v[100:115], v[172:175], v[120:123], v[100:115]
	v_add_f32_e32 v72, v78, v136
	v_add_f32_e32 v72, v79, v72
	v_add_f32_e32 v72, v80, v72
	v_add_f32_e32 v136, v81, v72
	v_cvt_pk_bf16_f32 v144, v76, v77
	v_cvt_pk_bf16_f32 v145, v78, v79
	ds_read_b64_tr_b16 v[72:73], v197 offset:29696
	ds_read_b64_tr_b16 v[74:75], v197 offset:30208
	v_mfma_f32_32x32x16_bf16 v[84:99], v[168:171], v[120:123], v[84:99]
	v_add_f32_e32 v76, v82, v136
	v_add_f32_e32 v76, v83, v76
	v_add_f32_e32 v76, v52, v76
	v_add_f32_e32 v136, v53, v76
	v_cvt_pk_bf16_f32 v146, v80, v81
	v_cvt_pk_bf16_f32 v147, v82, v83
	ds_read_b64_tr_b16 v[76:77], v197 offset:26624
	ds_read_b64_tr_b16 v[78:79], v197 offset:27136
	v_mfma_f32_32x32x16_bf16 v[100:115], v[164:167], v[124:127], v[100:115]
	v_add_f32_e32 v80, v54, v136
	v_add_f32_e32 v80, v55, v80
	v_cvt_pk_bf16_f32 v140, v52, v53
	v_add_f32_e32 v80, v56, v80
	v_cvt_pk_bf16_f32 v141, v54, v55
	v_add_f32_e32 v80, v57, v80
	ds_read_b64_tr_b16 v[52:53], v197 offset:30720
	ds_read_b64_tr_b16 v[54:55], v197 offset:31232
	v_mfma_f32_32x32x16_bf16 v[84:99], v[160:163], v[124:127], v[84:99]
	v_add_f32_e32 v80, v58, v80
	v_add_f32_e32 v80, v59, v80
	v_cvt_pk_bf16_f32 v142, v56, v57
	v_add_f32_e32 v80, v60, v80
	v_cvt_pk_bf16_f32 v143, v58, v59
	v_add_f32_e32 v80, v61, v80
	ds_read_b64_tr_b16 v[56:57], v197 offset:27648
	ds_read_b64_tr_b16 v[58:59], v197 offset:28160
	v_mfma_f32_32x32x16_bf16 v[100:115], v[156:159], v[128:131], v[100:115]
	v_add_f32_e32 v80, v62, v80
	v_add_f32_e32 v80, v63, v80
	v_cvt_pk_bf16_f32 v136, v60, v61
	v_add_f32_e32 v80, v64, v80
	v_cvt_pk_bf16_f32 v137, v62, v63
	v_add_f32_e32 v80, v65, v80
	ds_read_b64_tr_b16 v[60:61], v197 offset:31744
	ds_read_b64_tr_b16 v[62:63], v197 offset:32256
	v_mfma_f32_32x32x16_bf16 v[84:99], v[152:155], v[128:131], v[84:99]
	v_add_f32_e32 v80, v66, v80
	v_cvt_pk_bf16_f32 v138, v64, v65
	v_add_f32_e32 v80, v67, v80
	v_cvt_pk_bf16_f32 v139, v66, v67
	s_add_i32 s10, s25, s46
	s_mov_b32 m0, s10
	s_nop 0
	global_load_lds_dwordx4 v202, s[98:99]
	s_add_i32 s10, s24, s47
	s_mov_b32 m0, s10
	s_nop 0
	global_load_lds_dwordx4 v203, s[98:99]
	v_add_f32_e32 v204, v220, v80
.LBB0_799:
	s_waitcnt lgkmcnt(14)
	v_mfma_f32_32x32x16_bf16 v[20:35], v[148:151], v[184:187], v[20:35]
	v_exp_f32_e32 v100, v100
	v_exp_f32_e32 v101, v101
	v_exp_f32_e32 v102, v102
	v_exp_f32_e32 v103, v103
	s_waitcnt lgkmcnt(12)
	v_mfma_f32_32x32x16_bf16 v[4:19], v[148:151], v[180:183], v[4:19]
	v_exp_f32_e32 v104, v104
	v_exp_f32_e32 v105, v105
	v_exp_f32_e32 v106, v106
	v_exp_f32_e32 v107, v107
	v_add_u32_e32 v80, s24, v218
	ds_read_b128 v[64:67], v80
	ds_read_b128 v[180:183], v80 offset:512
	s_waitcnt lgkmcnt(12)
	v_mfma_f32_32x32x16_bf16 v[20:35], v[144:147], v[68:71], v[20:35]
	v_exp_f32_e32 v108, v108
	v_exp_f32_e32 v109, v109
	v_exp_f32_e32 v110, v110
	v_exp_f32_e32 v111, v111
	ds_read_b128 v[184:187], v80 offset:2048
	ds_read_b128 v[176:179], v80 offset:2560
	s_waitcnt lgkmcnt(12)
	v_mfma_f32_32x32x16_bf16 v[4:19], v[144:147], v[72:75], v[4:19]
	v_exp_f32_e32 v112, v112
	v_exp_f32_e32 v113, v113
	v_exp_f32_e32 v114, v114
	v_exp_f32_e32 v115, v115
	ds_read_b128 v[172:175], v80 offset:4096
	ds_read_b128 v[168:171], v80 offset:4608
	s_waitcnt lgkmcnt(12)
	v_mfma_f32_32x32x16_bf16 v[20:35], v[140:143], v[76:79], v[20:35]
	v_exp_f32_e32 v84, v84
	v_exp_f32_e32 v85, v85
	v_exp_f32_e32 v86, v86
	v_exp_f32_e32 v87, v87
	ds_read_b128 v[164:167], v80 offset:6144
	ds_read_b128 v[160:163], v80 offset:6656
	s_waitcnt lgkmcnt(12)
	v_mfma_f32_32x32x16_bf16 v[4:19], v[140:143], v[52:55], v[4:19]
	v_exp_f32_e32 v88, v88
	v_exp_f32_e32 v89, v89
	v_exp_f32_e32 v90, v90
	v_exp_f32_e32 v91, v91
	s_cmp_eq_u32 s101, 32
	s_cbranch_scc1 .Lattn0_rot
.Lattn0_rotback:
	v_bfe_i32 v196, v132, s101, 1
	v_bfi_b32 v246, v196, v222, v223
	s_waitcnt lgkmcnt(10)
	v_mfma_f32_32x32x16_bf16 v[20:35], v[136:139], v[56:59], v[20:35]
	v_exp_f32_e32 v92, v92
	v_exp_f32_e32 v93, v93
	v_exp_f32_e32 v94, v94
	v_exp_f32_e32 v95, v95
	v_mfma_f32_32x32x16_bf16 v[36:51], v[250:253], v[246:249], 0
	s_waitcnt lgkmcnt(8)
	v_mfma_f32_32x32x16_bf16 v[4:19], v[136:139], v[60:63], v[4:19]
	v_exp_f32_e32 v96, v96
	v_exp_f32_e32 v97, v97
	v_exp_f32_e32 v98, v98
	v_exp_f32_e32 v99, v99
	s_add_i32 s101, s101, 1
	s_add_i32 s10, s24, 0x2000
	s_cmpk_lg_i32 s24, 0x4000
	s_cselect_b32 s54, s10, 0
	s_waitcnt lgkmcnt(0)
	v_mfma_f32_32x32x16_bf16 v[68:83], v[64:67], v[116:119], v[36:51]
	v_mfma_f32_32x32x16_bf16 v[52:67], v[180:183], v[116:119], v[36:51]
	s_waitcnt vmcnt(2) lgkmcnt(0)
	s_barrier
.LBB0_801:
	v_add_u32_e32 v197, s25, v219
	ds_read_b64_tr_b16 v[152:153], v197 offset:24576
	ds_read_b64_tr_b16 v[154:155], v197 offset:25088
	v_add_f32_e32 v206, v100, v101
	v_add_f32_e32 v206, v102, v206
	v_add_f32_e32 v206, v103, v206
	v_cvt_pk_bf16_f32 v148, v100, v101
	v_add_f32_e32 v206, v104, v206
	v_cvt_pk_bf16_f32 v149, v102, v103
	v_add_f32_e32 v206, v105, v206
	ds_read_b64_tr_b16 v[156:157], v197 offset:28672
	ds_read_b64_tr_b16 v[158:159], v197 offset:29184
	v_add_f32_e32 v206, v106, v206
	v_add_f32_e32 v206, v107, v206
	v_add_f32_e32 v206, v108, v206
	v_add_f32_e32 v136, v109, v206
	v_cvt_pk_bf16_f32 v150, v104, v105
	v_cvt_pk_bf16_f32 v151, v106, v107
	ds_read_b64_tr_b16 v[100:101], v197 offset:25600
	ds_read_b64_tr_b16 v[102:103], v197 offset:26112
	v_mfma_f32_32x32x16_bf16 v[68:83], v[184:187], v[120:123], v[68:83]
	v_add_f32_e32 v104, v110, v136
	v_add_f32_e32 v104, v111, v104
	v_add_f32_e32 v104, v112, v104
	v_add_f32_e32 v136, v113, v104
	v_cvt_pk_bf16_f32 v144, v108, v109
	v_cvt_pk_bf16_f32 v145, v110, v111
	ds_read_b64_tr_b16 v[104:105], v197 offset:29696
	ds_read_b64_tr_b16 v[106:107], v197 offset:30208
	v_mfma_f32_32x32x16_bf16 v[52:67], v[176:179], v[120:123], v[52:67]
	v_add_f32_e32 v108, v114, v136
	v_add_f32_e32 v108, v115, v108
	v_add_f32_e32 v108, v84, v108
	v_add_f32_e32 v136, v85, v108
	v_cvt_pk_bf16_f32 v146, v112, v113
	v_cvt_pk_bf16_f32 v147, v114, v115
	ds_read_b64_tr_b16 v[108:109], v197 offset:26624
	ds_read_b64_tr_b16 v[110:111], v197 offset:27136
	v_mfma_f32_32x32x16_bf16 v[68:83], v[172:175], v[124:127], v[68:83]
	v_add_f32_e32 v112, v86, v136
	v_add_f32_e32 v112, v87, v112
	v_cvt_pk_bf16_f32 v140, v84, v85
	v_add_f32_e32 v112, v88, v112
	v_cvt_pk_bf16_f32 v141, v86, v87
	v_add_f32_e32 v112, v89, v112
	ds_read_b64_tr_b16 v[84:85], v197 offset:30720
	ds_read_b64_tr_b16 v[86:87], v197 offset:31232
	v_mfma_f32_32x32x16_bf16 v[52:67], v[168:171], v[124:127], v[52:67]
	v_add_f32_e32 v112, v90, v112
	v_add_f32_e32 v112, v91, v112
	v_cvt_pk_bf16_f32 v142, v88, v89
	v_add_f32_e32 v112, v92, v112
	v_cvt_pk_bf16_f32 v143, v90, v91
	v_add_f32_e32 v112, v93, v112
	ds_read_b64_tr_b16 v[88:89], v197 offset:27648
	ds_read_b64_tr_b16 v[90:91], v197 offset:28160
	v_mfma_f32_32x32x16_bf16 v[68:83], v[164:167], v[128:131], v[68:83]
	v_add_f32_e32 v112, v94, v112
	v_add_f32_e32 v112, v95, v112
	v_cvt_pk_bf16_f32 v136, v92, v93
	v_add_f32_e32 v112, v96, v112
	v_cvt_pk_bf16_f32 v137, v94, v95
	v_add_f32_e32 v112, v97, v112
	ds_read_b64_tr_b16 v[92:93], v197 offset:31744
	ds_read_b64_tr_b16 v[94:95], v197 offset:32256
	v_mfma_f32_32x32x16_bf16 v[52:67], v[160:163], v[128:131], v[52:67]
	v_add_f32_e32 v112, v98, v112
	v_cvt_pk_bf16_f32 v138, v96, v97
	v_add_f32_e32 v112, v99, v112
	v_cvt_pk_bf16_f32 v139, v98, v99
	v_add_f32_e32 v220, v204, v112
	s_add_i32 s10, s24, s46
	s_mov_b32 m0, s10
	s_nop 0
	global_load_lds_dwordx4 v198, s[98:99]
	s_add_i32 s10, s54, s47
	s_mov_b32 m0, s10
	s_nop 0
	global_load_lds_dwordx4 v199, s[98:99]
.LBB0_802:
	s_waitcnt lgkmcnt(14)
	v_mfma_f32_32x32x16_bf16 v[20:35], v[148:151], v[152:155], v[20:35]
	v_exp_f32_e32 v68, v68
	v_exp_f32_e32 v69, v69
	v_exp_f32_e32 v70, v70
	v_exp_f32_e32 v71, v71
	s_waitcnt lgkmcnt(12)
	v_mfma_f32_32x32x16_bf16 v[4:19], v[148:151], v[156:159], v[4:19]
	v_exp_f32_e32 v72, v72
	v_exp_f32_e32 v73, v73
	v_exp_f32_e32 v74, v74
	v_exp_f32_e32 v75, v75
	v_add_u32_e32 v96, s54, v218
	ds_read_b128 v[180:183], v96
	ds_read_b128 v[176:179], v96 offset:512
	s_waitcnt lgkmcnt(12)
	v_mfma_f32_32x32x16_bf16 v[20:35], v[144:147], v[100:103], v[20:35]
	v_exp_f32_e32 v76, v76
	v_exp_f32_e32 v77, v77
	v_exp_f32_e32 v78, v78
	v_exp_f32_e32 v79, v79
	ds_read_b128 v[172:175], v96 offset:2048
	ds_read_b128 v[168:171], v96 offset:2560
	s_waitcnt lgkmcnt(12)
	v_mfma_f32_32x32x16_bf16 v[4:19], v[144:147], v[104:107], v[4:19]
	v_exp_f32_e32 v80, v80
	v_exp_f32_e32 v81, v81
	v_exp_f32_e32 v82, v82
	v_exp_f32_e32 v83, v83
	ds_read_b128 v[164:167], v96 offset:4096
	ds_read_b128 v[160:163], v96 offset:4608
	s_waitcnt lgkmcnt(12)
	v_mfma_f32_32x32x16_bf16 v[20:35], v[140:143], v[108:111], v[20:35]
	v_exp_f32_e32 v52, v52
	v_exp_f32_e32 v53, v53
	v_exp_f32_e32 v54, v54
	v_exp_f32_e32 v55, v55
	ds_read_b128 v[156:159], v96 offset:6144
	ds_read_b128 v[152:155], v96 offset:6656
	s_waitcnt lgkmcnt(12)
	v_mfma_f32_32x32x16_bf16 v[4:19], v[140:143], v[84:87], v[4:19]
	v_exp_f32_e32 v56, v56
	v_exp_f32_e32 v57, v57
	v_exp_f32_e32 v58, v58
	v_exp_f32_e32 v59, v59
	v_bfe_i32 v196, v132, s101, 1
	v_bfi_b32 v246, v196, v222, v223
	s_waitcnt lgkmcnt(10)
	v_mfma_f32_32x32x16_bf16 v[20:35], v[136:139], v[88:91], v[20:35]
	v_exp_f32_e32 v60, v60
	v_exp_f32_e32 v61, v61
	v_exp_f32_e32 v62, v62
	v_exp_f32_e32 v63, v63
	v_mfma_f32_32x32x16_bf16 v[36:51], v[250:253], v[246:249], 0
	s_waitcnt lgkmcnt(8)
	v_mfma_f32_32x32x16_bf16 v[4:19], v[136:139], v[92:95], v[4:19]
	v_exp_f32_e32 v64, v64
	v_exp_f32_e32 v65, v65
	v_exp_f32_e32 v66, v66
	v_exp_f32_e32 v67, v67
	s_add_i32 s101, s101, 1
	s_add_i32 s0, s0, 2
	s_add_i32 s10, s54, 0x2000
	s_cmpk_lg_i32 s54, 0x4000
	s_cselect_b32 s42, s10, 0
	s_add_u32 s98, s98, s80
	s_addc_u32 s99, s99, s81
	s_cmp_ge_i32 s0, s1
	s_cbranch_scc1 .Lattn0_exit
	s_mov_b32 s10, s24
	s_mov_b32 s25, s54
	s_mov_b32 s24, s42
	s_branch .Lattn0_head
